# fast epilogue for the RWKV LoRA-2 GEMM column groups 0/1: bias vectors loaded once per tile, packed sigmoid math, no per-row-block vmcnt drain
# speedup vs baseline: 1.1711x; 1.0066x over previous
; __device__ __forceinline__ u32x4 pack8(f32x4 a, f32x4 b) { u32x4 w; w.x = pk2(a[0], a[1]); w.y = pk2(a[2], a[3]); w.z = pk2(b[0], b[1]); w.w = pk2(b[2], b[3]); return w; }
; __device__ __forceinline__ float sigmoidf_(float x) { return __builtin_amdgcn_rcpf(1.0f + __expf(-x)); }
;     __device__ __forceinline__ void operator()(const f32x4 (&acc)[2][2][4][2], const Unit& u, int wr, int wc, int fr, int fq) const {
;     ...
;                     } else if (mode == E_LORA2) {
;                         const int grp = u.pn >> 2, c = col & 1023;
;                         const size_t off = (size_t)rowg * 1024 + c;
;                         if (grp == 0) {
;                             const f32x4 ba = *(const f32x4*)(bias0 + c), bb = *(const f32x4*)(bias0 + c + 4);
; #pragma unroll
;                             for (int jj = 0; jj < 4; ++jj) { v0[jj] = sigmoidf_(v0[jj] + ba[jj]) * 0.6065306597f; v1[jj] = sigmoidf_(v1[jj] + bb[jj]) * 0.6065306597f; }
;                             *(u32x4*)((h16*)out + off) = pack8(v0, v1);
;                         } else if (grp == 1) {
;                             const f32x4 ba = *(const f32x4*)(bias1 + c), bb = *(const f32x4*)(bias1 + c + 4);
; #pragma unroll
;                             for (int jj = 0; jj < 4; ++jj) { v0[jj] = sigmoidf_(v0[jj] + ba[jj]); v1[jj] = sigmoidf_(v1[jj] + bb[jj]); }
;                             *(u32x4*)((h16*)out + (size_t)MTOK * 1024 + off) = pack8(v0, v1);
.Llora_fast:
	v_readlane_b32 s34, v253, 59
	v_readlane_b32 s35, v253, 60
	v_readlane_b32 s36, v253, 61
	v_readlane_b32 s37, v253, 62
	v_readlane_b32 s38, v252, 45
	v_readlane_b32 s39, v252, 46
	v_readlane_b32 s86, v252, 47
	v_readlane_b32 s87, v252, 48
	s_cmp_eq_u32 s0, 0
	s_cselect_b32 s34, s34, s36
	s_cselect_b32 s35, s35, s37
	s_cselect_b32 s38, s38, s86
	s_cselect_b32 s39, s39, s87
	s_cselect_b32 s86, 0x3f1b4598, 1.0
	s_mov_b32 s87, s86
	v_and_b32_e32 v128, 0x3ff, v216
	v_lshlrev_b32_e32 v129, 2, v128
	global_load_dwordx4 v[132:135], v129, s[34:35]
	global_load_dwordx4 v[136:139], v129, s[34:35] offset:16
	global_load_dwordx4 v[140:143], v129, s[34:35] offset:512
	global_load_dwordx4 v[144:147], v129, s[34:35] offset:528
	s_movk_i32 s33, 0x800
	v_lshlrev_b32_e32 v130, 1, v128
	v_mov_b32_e32 v131, v197
	v_mad_u64_u32 v[164:165], s[0:1], v240, s33, v[130:131]
	s_mov_b32 s34, 0xbfb8aa3b
	s_mov_b32 s35, 0xbfb8aa3b
	s_mov_b32 s36, 1.0
	s_mov_b32 s37, 1.0
	v_lshl_add_u64 v[164:165], s[38:39], 0, v[164:165]
	s_mov_b32 s0, 0x8000
	s_mov_b32 s1, 0
	s_mov_b32 s38, 0x28000
	s_mov_b32 s39, 0
	s_waitcnt vmcnt(0)
	v_pk_add_f32 v[124:125], v[124:125], v[132:133]
	v_pk_add_f32 v[126:127], v[126:127], v[134:135]
	v_pk_add_f32 v[120:121], v[120:121], v[136:137]
	v_pk_add_f32 v[122:123], v[122:123], v[138:139]
	v_pk_mul_f32 v[148:149], v[124:125], s[34:35]
	v_pk_mul_f32 v[150:151], v[126:127], s[34:35]
	v_pk_mul_f32 v[152:153], v[120:121], s[34:35]
	v_pk_mul_f32 v[154:155], v[122:123], s[34:35]
	v_exp_f32_e32 v148, v148
	v_exp_f32_e32 v150, v150
	v_exp_f32_e32 v152, v152
	v_exp_f32_e32 v154, v154
	v_exp_f32_e32 v149, v149
	v_exp_f32_e32 v151, v151
	v_exp_f32_e32 v153, v153
	v_exp_f32_e32 v155, v155
	v_pk_add_f32 v[148:149], v[148:149], s[36:37]
	v_pk_add_f32 v[150:151], v[150:151], s[36:37]
	v_pk_add_f32 v[152:153], v[152:153], s[36:37]
	v_pk_add_f32 v[154:155], v[154:155], s[36:37]
	v_rcp_f32_e32 v148, v148
	v_rcp_f32_e32 v150, v150
	v_rcp_f32_e32 v152, v152
	v_rcp_f32_e32 v154, v154
	v_rcp_f32_e32 v149, v149
	v_rcp_f32_e32 v151, v151
	v_rcp_f32_e32 v153, v153
	v_rcp_f32_e32 v155, v155
	v_pk_mul_f32 v[148:149], v[148:149], s[86:87]
	v_pk_mul_f32 v[150:151], v[150:151], s[86:87]
	v_pk_mul_f32 v[152:153], v[152:153], s[86:87]
	v_pk_mul_f32 v[154:155], v[154:155], s[86:87]
	s_nop 0
	v_cvt_pk_f16_f32 v156, v148, v149
	v_cvt_pk_f16_f32 v157, v150, v151
	v_cvt_pk_f16_f32 v158, v152, v153
	v_cvt_pk_f16_f32 v159, v154, v155
	v_lshl_add_u64 v[166:167], v[164:165], 0, s[0:1]
	global_store_dwordx4 v[164:165], v[156:159], off
	v_pk_add_f32 v[116:117], v[116:117], v[140:141]
	v_pk_add_f32 v[118:119], v[118:119], v[142:143]
	v_pk_add_f32 v[112:113], v[112:113], v[144:145]
	v_pk_add_f32 v[114:115], v[114:115], v[146:147]
	v_pk_mul_f32 v[148:149], v[116:117], s[34:35]
	v_pk_mul_f32 v[150:151], v[118:119], s[34:35]
	v_pk_mul_f32 v[152:153], v[112:113], s[34:35]
	v_pk_mul_f32 v[154:155], v[114:115], s[34:35]
	v_exp_f32_e32 v148, v148
	v_exp_f32_e32 v150, v150
	v_exp_f32_e32 v152, v152
	v_exp_f32_e32 v154, v154
	v_exp_f32_e32 v149, v149
	v_exp_f32_e32 v151, v151
	v_exp_f32_e32 v153, v153
	v_exp_f32_e32 v155, v155
	v_pk_add_f32 v[148:149], v[148:149], s[36:37]
	v_pk_add_f32 v[150:151], v[150:151], s[36:37]
	v_pk_add_f32 v[152:153], v[152:153], s[36:37]
	v_pk_add_f32 v[154:155], v[154:155], s[36:37]
	v_rcp_f32_e32 v148, v148
	v_rcp_f32_e32 v150, v150
	v_rcp_f32_e32 v152, v152
	v_rcp_f32_e32 v154, v154
	v_rcp_f32_e32 v149, v149
	v_rcp_f32_e32 v151, v151
	v_rcp_f32_e32 v153, v153
	v_rcp_f32_e32 v155, v155
	v_pk_mul_f32 v[148:149], v[148:149], s[86:87]
	v_pk_mul_f32 v[150:151], v[150:151], s[86:87]
	v_pk_mul_f32 v[152:153], v[152:153], s[86:87]
	v_pk_mul_f32 v[154:155], v[154:155], s[86:87]
	s_nop 0
	v_cvt_pk_f16_f32 v160, v148, v149
	v_cvt_pk_f16_f32 v161, v150, v151
	v_cvt_pk_f16_f32 v162, v152, v153
	v_cvt_pk_f16_f32 v163, v154, v155
	global_store_dwordx4 v[164:165], v[160:163], off offset:256
	v_pk_add_f32 v[108:109], v[108:109], v[132:133]
	v_pk_add_f32 v[110:111], v[110:111], v[134:135]
	v_pk_add_f32 v[104:105], v[104:105], v[136:137]
	v_pk_add_f32 v[106:107], v[106:107], v[138:139]
	v_pk_mul_f32 v[148:149], v[108:109], s[34:35]
	v_pk_mul_f32 v[150:151], v[110:111], s[34:35]
	v_pk_mul_f32 v[152:153], v[104:105], s[34:35]
	v_pk_mul_f32 v[154:155], v[106:107], s[34:35]
	v_exp_f32_e32 v148, v148
	v_exp_f32_e32 v150, v150
	v_exp_f32_e32 v152, v152
	v_exp_f32_e32 v154, v154
	v_exp_f32_e32 v149, v149
	v_exp_f32_e32 v151, v151
	v_exp_f32_e32 v153, v153
	v_exp_f32_e32 v155, v155
	v_pk_add_f32 v[148:149], v[148:149], s[36:37]
	v_pk_add_f32 v[150:151], v[150:151], s[36:37]
	v_pk_add_f32 v[152:153], v[152:153], s[36:37]
	v_pk_add_f32 v[154:155], v[154:155], s[36:37]
	v_rcp_f32_e32 v148, v148
	v_rcp_f32_e32 v150, v150
	v_rcp_f32_e32 v152, v152
	v_rcp_f32_e32 v154, v154
	v_rcp_f32_e32 v149, v149
	v_rcp_f32_e32 v151, v151
	v_rcp_f32_e32 v153, v153
	v_rcp_f32_e32 v155, v155
	v_pk_mul_f32 v[148:149], v[148:149], s[86:87]
	v_pk_mul_f32 v[150:151], v[150:151], s[86:87]
	v_pk_mul_f32 v[152:153], v[152:153], s[86:87]
	v_pk_mul_f32 v[154:155], v[154:155], s[86:87]
	s_nop 0
	v_cvt_pk_f16_f32 v156, v148, v149
	v_cvt_pk_f16_f32 v157, v150, v151
	v_cvt_pk_f16_f32 v158, v152, v153
	v_cvt_pk_f16_f32 v159, v154, v155
	v_lshl_add_u64 v[164:165], v[166:167], 0, s[0:1]
	global_store_dwordx4 v[166:167], v[156:159], off
	v_pk_add_f32 v[100:101], v[100:101], v[140:141]
	v_pk_add_f32 v[102:103], v[102:103], v[142:143]
	v_pk_add_f32 v[96:97], v[96:97], v[144:145]
	v_pk_add_f32 v[98:99], v[98:99], v[146:147]
	v_pk_mul_f32 v[148:149], v[100:101], s[34:35]
	v_pk_mul_f32 v[150:151], v[102:103], s[34:35]
; __device__ __forceinline__ u32x4 pack8(f32x4 a, f32x4 b) { u32x4 w; w.x = pk2(a[0], a[1]); w.y = pk2(a[2], a[3]); w.z = pk2(b[0], b[1]); w.w = pk2(b[2], b[3]); return w; }
; __device__ __forceinline__ float sigmoidf_(float x) { return __builtin_amdgcn_rcpf(1.0f + __expf(-x)); }
;     __device__ __forceinline__ void operator()(const f32x4 (&acc)[2][2][4][2], const Unit& u, int wr, int wc, int fr, int fq) const {
;     ...
;                     } else if (mode == E_LORA2) {
;                         const int grp = u.pn >> 2, c = col & 1023;
;                         const size_t off = (size_t)rowg * 1024 + c;
;                         if (grp == 0) {
;                             const f32x4 ba = *(const f32x4*)(bias0 + c), bb = *(const f32x4*)(bias0 + c + 4);
; #pragma unroll
;                             for (int jj = 0; jj < 4; ++jj) { v0[jj] = sigmoidf_(v0[jj] + ba[jj]) * 0.6065306597f; v1[jj] = sigmoidf_(v1[jj] + bb[jj]) * 0.6065306597f; }
;                             *(u32x4*)((h16*)out + off) = pack8(v0, v1);
;                         } else if (grp == 1) {
;                             const f32x4 ba = *(const f32x4*)(bias1 + c), bb = *(const f32x4*)(bias1 + c + 4);
; #pragma unroll
;                             for (int jj = 0; jj < 4; ++jj) { v0[jj] = sigmoidf_(v0[jj] + ba[jj]); v1[jj] = sigmoidf_(v1[jj] + bb[jj]); }
;                             *(u32x4*)((h16*)out + (size_t)MTOK * 1024 + off) = pack8(v0, v1);
	v_pk_mul_f32 v[152:153], v[96:97], s[34:35]
	v_pk_mul_f32 v[154:155], v[98:99], s[34:35]
	v_exp_f32_e32 v148, v148
	v_exp_f32_e32 v150, v150
	v_exp_f32_e32 v152, v152
	v_exp_f32_e32 v154, v154
	v_exp_f32_e32 v149, v149
	v_exp_f32_e32 v151, v151
	v_exp_f32_e32 v153, v153
	v_exp_f32_e32 v155, v155
	v_pk_add_f32 v[148:149], v[148:149], s[36:37]
	v_pk_add_f32 v[150:151], v[150:151], s[36:37]
	v_pk_add_f32 v[152:153], v[152:153], s[36:37]
	v_pk_add_f32 v[154:155], v[154:155], s[36:37]
	v_rcp_f32_e32 v148, v148
	v_rcp_f32_e32 v150, v150
	v_rcp_f32_e32 v152, v152
	v_rcp_f32_e32 v154, v154
	v_rcp_f32_e32 v149, v149
	v_rcp_f32_e32 v151, v151
	v_rcp_f32_e32 v153, v153
	v_rcp_f32_e32 v155, v155
	v_pk_mul_f32 v[148:149], v[148:149], s[86:87]
	v_pk_mul_f32 v[150:151], v[150:151], s[86:87]
	v_pk_mul_f32 v[152:153], v[152:153], s[86:87]
	v_pk_mul_f32 v[154:155], v[154:155], s[86:87]
	s_nop 0
	v_cvt_pk_f16_f32 v160, v148, v149
	v_cvt_pk_f16_f32 v161, v150, v151
	v_cvt_pk_f16_f32 v162, v152, v153
	v_cvt_pk_f16_f32 v163, v154, v155
	global_store_dwordx4 v[166:167], v[160:163], off offset:256
	v_pk_add_f32 v[92:93], v[92:93], v[132:133]
	v_pk_add_f32 v[94:95], v[94:95], v[134:135]
	v_pk_add_f32 v[88:89], v[88:89], v[136:137]
	v_pk_add_f32 v[90:91], v[90:91], v[138:139]
	v_pk_mul_f32 v[148:149], v[92:93], s[34:35]
	v_pk_mul_f32 v[150:151], v[94:95], s[34:35]
	v_pk_mul_f32 v[152:153], v[88:89], s[34:35]
	v_pk_mul_f32 v[154:155], v[90:91], s[34:35]
	v_exp_f32_e32 v148, v148
	v_exp_f32_e32 v150, v150
	v_exp_f32_e32 v152, v152
	v_exp_f32_e32 v154, v154
	v_exp_f32_e32 v149, v149
	v_exp_f32_e32 v151, v151
	v_exp_f32_e32 v153, v153
	v_exp_f32_e32 v155, v155
	v_pk_add_f32 v[148:149], v[148:149], s[36:37]
	v_pk_add_f32 v[150:151], v[150:151], s[36:37]
	v_pk_add_f32 v[152:153], v[152:153], s[36:37]
	v_pk_add_f32 v[154:155], v[154:155], s[36:37]
	v_rcp_f32_e32 v148, v148
	v_rcp_f32_e32 v150, v150
	v_rcp_f32_e32 v152, v152
	v_rcp_f32_e32 v154, v154
	v_rcp_f32_e32 v149, v149
	v_rcp_f32_e32 v151, v151
	v_rcp_f32_e32 v153, v153
	v_rcp_f32_e32 v155, v155
	v_pk_mul_f32 v[148:149], v[148:149], s[86:87]
	v_pk_mul_f32 v[150:151], v[150:151], s[86:87]
	v_pk_mul_f32 v[152:153], v[152:153], s[86:87]
	v_pk_mul_f32 v[154:155], v[154:155], s[86:87]
	s_nop 0
	v_cvt_pk_f16_f32 v156, v148, v149
	v_cvt_pk_f16_f32 v157, v150, v151
	v_cvt_pk_f16_f32 v158, v152, v153
	v_cvt_pk_f16_f32 v159, v154, v155
	v_lshl_add_u64 v[166:167], v[164:165], 0, s[0:1]
	global_store_dwordx4 v[164:165], v[156:159], off
	v_pk_add_f32 v[84:85], v[84:85], v[140:141]
	v_pk_add_f32 v[86:87], v[86:87], v[142:143]
	v_pk_add_f32 v[80:81], v[80:81], v[144:145]
	v_pk_add_f32 v[82:83], v[82:83], v[146:147]
	v_pk_mul_f32 v[148:149], v[84:85], s[34:35]
	v_pk_mul_f32 v[150:151], v[86:87], s[34:35]
	v_pk_mul_f32 v[152:153], v[80:81], s[34:35]
	v_pk_mul_f32 v[154:155], v[82:83], s[34:35]
	v_exp_f32_e32 v148, v148
	v_exp_f32_e32 v150, v150
	v_exp_f32_e32 v152, v152
	v_exp_f32_e32 v154, v154
	v_exp_f32_e32 v149, v149
	v_exp_f32_e32 v151, v151
	v_exp_f32_e32 v153, v153
	v_exp_f32_e32 v155, v155
	v_pk_add_f32 v[148:149], v[148:149], s[36:37]
	v_pk_add_f32 v[150:151], v[150:151], s[36:37]
	v_pk_add_f32 v[152:153], v[152:153], s[36:37]
	v_pk_add_f32 v[154:155], v[154:155], s[36:37]
	v_rcp_f32_e32 v148, v148
	v_rcp_f32_e32 v150, v150
	v_rcp_f32_e32 v152, v152
	v_rcp_f32_e32 v154, v154
	v_rcp_f32_e32 v149, v149
	v_rcp_f32_e32 v151, v151
	v_rcp_f32_e32 v153, v153
	v_rcp_f32_e32 v155, v155
	v_pk_mul_f32 v[148:149], v[148:149], s[86:87]
	v_pk_mul_f32 v[150:151], v[150:151], s[86:87]
	v_pk_mul_f32 v[152:153], v[152:153], s[86:87]
	v_pk_mul_f32 v[154:155], v[154:155], s[86:87]
	s_nop 0
	v_cvt_pk_f16_f32 v160, v148, v149
	v_cvt_pk_f16_f32 v161, v150, v151
	v_cvt_pk_f16_f32 v162, v152, v153
	v_cvt_pk_f16_f32 v163, v154, v155
	global_store_dwordx4 v[164:165], v[160:163], off offset:256
	v_pk_add_f32 v[76:77], v[76:77], v[132:133]
	v_pk_add_f32 v[78:79], v[78:79], v[134:135]
	v_pk_add_f32 v[72:73], v[72:73], v[136:137]
	v_pk_add_f32 v[74:75], v[74:75], v[138:139]
	v_pk_mul_f32 v[148:149], v[76:77], s[34:35]
	v_pk_mul_f32 v[150:151], v[78:79], s[34:35]
	v_pk_mul_f32 v[152:153], v[72:73], s[34:35]
	v_pk_mul_f32 v[154:155], v[74:75], s[34:35]
	v_exp_f32_e32 v148, v148
	v_exp_f32_e32 v150, v150
	v_exp_f32_e32 v152, v152
	v_exp_f32_e32 v154, v154
	v_exp_f32_e32 v149, v149
	v_exp_f32_e32 v151, v151
	v_exp_f32_e32 v153, v153
	v_exp_f32_e32 v155, v155
	v_pk_add_f32 v[148:149], v[148:149], s[36:37]
	v_pk_add_f32 v[150:151], v[150:151], s[36:37]
	v_pk_add_f32 v[152:153], v[152:153], s[36:37]
	v_pk_add_f32 v[154:155], v[154:155], s[36:37]
	v_rcp_f32_e32 v148, v148
	v_rcp_f32_e32 v150, v150
	v_rcp_f32_e32 v152, v152
	v_rcp_f32_e32 v154, v154
	v_rcp_f32_e32 v149, v149
	v_rcp_f32_e32 v151, v151
	v_rcp_f32_e32 v153, v153
	v_rcp_f32_e32 v155, v155
	v_pk_mul_f32 v[148:149], v[148:149], s[86:87]
	v_pk_mul_f32 v[150:151], v[150:151], s[86:87]
	v_pk_mul_f32 v[152:153], v[152:153], s[86:87]
	v_pk_mul_f32 v[154:155], v[154:155], s[86:87]
	s_nop 0
	v_cvt_pk_f16_f32 v156, v148, v149
	v_cvt_pk_f16_f32 v157, v150, v151
	v_cvt_pk_f16_f32 v158, v152, v153
	v_cvt_pk_f16_f32 v159, v154, v155
	v_lshl_add_u64 v[164:165], v[166:167], 0, s[38:39]
	global_store_dwordx4 v[166:167], v[156:159], off
	v_pk_add_f32 v[68:69], v[68:69], v[140:141]
	v_pk_add_f32 v[70:71], v[70:71], v[142:143]
	v_pk_add_f32 v[64:65], v[64:65], v[144:145]
	v_pk_add_f32 v[66:67], v[66:67], v[146:147]
	v_pk_mul_f32 v[148:149], v[68:69], s[34:35]
	v_pk_mul_f32 v[150:151], v[70:71], s[34:35]
	v_pk_mul_f32 v[152:153], v[64:65], s[34:35]
	v_pk_mul_f32 v[154:155], v[66:67], s[34:35]
	v_exp_f32_e32 v148, v148
; __device__ __forceinline__ u32x4 pack8(f32x4 a, f32x4 b) { u32x4 w; w.x = pk2(a[0], a[1]); w.y = pk2(a[2], a[3]); w.z = pk2(b[0], b[1]); w.w = pk2(b[2], b[3]); return w; }
; __device__ __forceinline__ float sigmoidf_(float x) { return __builtin_amdgcn_rcpf(1.0f + __expf(-x)); }
;     __device__ __forceinline__ void operator()(const f32x4 (&acc)[2][2][4][2], const Unit& u, int wr, int wc, int fr, int fq) const {
;     ...
;                     } else if (mode == E_LORA2) {
;                         const int grp = u.pn >> 2, c = col & 1023;
;                         const size_t off = (size_t)rowg * 1024 + c;
;                         if (grp == 0) {
;                             const f32x4 ba = *(const f32x4*)(bias0 + c), bb = *(const f32x4*)(bias0 + c + 4);
; #pragma unroll
;                             for (int jj = 0; jj < 4; ++jj) { v0[jj] = sigmoidf_(v0[jj] + ba[jj]) * 0.6065306597f; v1[jj] = sigmoidf_(v1[jj] + bb[jj]) * 0.6065306597f; }
;                             *(u32x4*)((h16*)out + off) = pack8(v0, v1);
;                         } else if (grp == 1) {
;                             const f32x4 ba = *(const f32x4*)(bias1 + c), bb = *(const f32x4*)(bias1 + c + 4);
; #pragma unroll
;                             for (int jj = 0; jj < 4; ++jj) { v0[jj] = sigmoidf_(v0[jj] + ba[jj]); v1[jj] = sigmoidf_(v1[jj] + bb[jj]); }
;                             *(u32x4*)((h16*)out + (size_t)MTOK * 1024 + off) = pack8(v0, v1);
	v_exp_f32_e32 v150, v150
	v_exp_f32_e32 v152, v152
	v_exp_f32_e32 v154, v154
	v_exp_f32_e32 v149, v149
	v_exp_f32_e32 v151, v151
	v_exp_f32_e32 v153, v153
	v_exp_f32_e32 v155, v155
	v_pk_add_f32 v[148:149], v[148:149], s[36:37]
	v_pk_add_f32 v[150:151], v[150:151], s[36:37]
	v_pk_add_f32 v[152:153], v[152:153], s[36:37]
	v_pk_add_f32 v[154:155], v[154:155], s[36:37]
	v_rcp_f32_e32 v148, v148
	v_rcp_f32_e32 v150, v150
	v_rcp_f32_e32 v152, v152
	v_rcp_f32_e32 v154, v154
	v_rcp_f32_e32 v149, v149
	v_rcp_f32_e32 v151, v151
	v_rcp_f32_e32 v153, v153
	v_rcp_f32_e32 v155, v155
	v_pk_mul_f32 v[148:149], v[148:149], s[86:87]
	v_pk_mul_f32 v[150:151], v[150:151], s[86:87]
	v_pk_mul_f32 v[152:153], v[152:153], s[86:87]
	v_pk_mul_f32 v[154:155], v[154:155], s[86:87]
	s_nop 0
	v_cvt_pk_f16_f32 v160, v148, v149
	v_cvt_pk_f16_f32 v161, v150, v151
	v_cvt_pk_f16_f32 v162, v152, v153
	v_cvt_pk_f16_f32 v163, v154, v155
	global_store_dwordx4 v[166:167], v[160:163], off offset:256
	v_pk_add_f32 v[60:61], v[60:61], v[132:133]
	v_pk_add_f32 v[62:63], v[62:63], v[134:135]
	v_pk_add_f32 v[56:57], v[56:57], v[136:137]
	v_pk_add_f32 v[58:59], v[58:59], v[138:139]
	v_pk_mul_f32 v[148:149], v[60:61], s[34:35]
	v_pk_mul_f32 v[150:151], v[62:63], s[34:35]
	v_pk_mul_f32 v[152:153], v[56:57], s[34:35]
	v_pk_mul_f32 v[154:155], v[58:59], s[34:35]
	v_exp_f32_e32 v148, v148
	v_exp_f32_e32 v150, v150
	v_exp_f32_e32 v152, v152
	v_exp_f32_e32 v154, v154
	v_exp_f32_e32 v149, v149
	v_exp_f32_e32 v151, v151
	v_exp_f32_e32 v153, v153
	v_exp_f32_e32 v155, v155
	v_pk_add_f32 v[148:149], v[148:149], s[36:37]
	v_pk_add_f32 v[150:151], v[150:151], s[36:37]
	v_pk_add_f32 v[152:153], v[152:153], s[36:37]
	v_pk_add_f32 v[154:155], v[154:155], s[36:37]
	v_rcp_f32_e32 v148, v148
	v_rcp_f32_e32 v150, v150
	v_rcp_f32_e32 v152, v152
	v_rcp_f32_e32 v154, v154
	v_rcp_f32_e32 v149, v149
	v_rcp_f32_e32 v151, v151
	v_rcp_f32_e32 v153, v153
	v_rcp_f32_e32 v155, v155
	v_pk_mul_f32 v[148:149], v[148:149], s[86:87]
	v_pk_mul_f32 v[150:151], v[150:151], s[86:87]
	v_pk_mul_f32 v[152:153], v[152:153], s[86:87]
	v_pk_mul_f32 v[154:155], v[154:155], s[86:87]
	s_nop 0
	v_cvt_pk_f16_f32 v156, v148, v149
	v_cvt_pk_f16_f32 v157, v150, v151
	v_cvt_pk_f16_f32 v158, v152, v153
	v_cvt_pk_f16_f32 v159, v154, v155
	v_lshl_add_u64 v[166:167], v[164:165], 0, s[0:1]
	global_store_dwordx4 v[164:165], v[156:159], off
	v_pk_add_f32 v[52:53], v[52:53], v[140:141]
	v_pk_add_f32 v[54:55], v[54:55], v[142:143]
	v_pk_add_f32 v[48:49], v[48:49], v[144:145]
	v_pk_add_f32 v[50:51], v[50:51], v[146:147]
	v_pk_mul_f32 v[148:149], v[52:53], s[34:35]
	v_pk_mul_f32 v[150:151], v[54:55], s[34:35]
	v_pk_mul_f32 v[152:153], v[48:49], s[34:35]
	v_pk_mul_f32 v[154:155], v[50:51], s[34:35]
	v_exp_f32_e32 v148, v148
	v_exp_f32_e32 v150, v150
	v_exp_f32_e32 v152, v152
	v_exp_f32_e32 v154, v154
	v_exp_f32_e32 v149, v149
	v_exp_f32_e32 v151, v151
	v_exp_f32_e32 v153, v153
	v_exp_f32_e32 v155, v155
	v_pk_add_f32 v[148:149], v[148:149], s[36:37]
	v_pk_add_f32 v[150:151], v[150:151], s[36:37]
	v_pk_add_f32 v[152:153], v[152:153], s[36:37]
	v_pk_add_f32 v[154:155], v[154:155], s[36:37]
	v_rcp_f32_e32 v148, v148
	v_rcp_f32_e32 v150, v150
	v_rcp_f32_e32 v152, v152
	v_rcp_f32_e32 v154, v154
	v_rcp_f32_e32 v149, v149
	v_rcp_f32_e32 v151, v151
	v_rcp_f32_e32 v153, v153
	v_rcp_f32_e32 v155, v155
	v_pk_mul_f32 v[148:149], v[148:149], s[86:87]
	v_pk_mul_f32 v[150:151], v[150:151], s[86:87]
	v_pk_mul_f32 v[152:153], v[152:153], s[86:87]
	v_pk_mul_f32 v[154:155], v[154:155], s[86:87]
	s_nop 0
	v_cvt_pk_f16_f32 v160, v148, v149
	v_cvt_pk_f16_f32 v161, v150, v151
	v_cvt_pk_f16_f32 v162, v152, v153
	v_cvt_pk_f16_f32 v163, v154, v155
	global_store_dwordx4 v[164:165], v[160:163], off offset:256
	v_pk_add_f32 v[44:45], v[44:45], v[132:133]
	v_pk_add_f32 v[46:47], v[46:47], v[134:135]
	v_pk_add_f32 v[40:41], v[40:41], v[136:137]
	v_pk_add_f32 v[42:43], v[42:43], v[138:139]
	v_pk_mul_f32 v[148:149], v[44:45], s[34:35]
	v_pk_mul_f32 v[150:151], v[46:47], s[34:35]
	v_pk_mul_f32 v[152:153], v[40:41], s[34:35]
	v_pk_mul_f32 v[154:155], v[42:43], s[34:35]
	v_exp_f32_e32 v148, v148
	v_exp_f32_e32 v150, v150
	v_exp_f32_e32 v152, v152
	v_exp_f32_e32 v154, v154
	v_exp_f32_e32 v149, v149
	v_exp_f32_e32 v151, v151
	v_exp_f32_e32 v153, v153
	v_exp_f32_e32 v155, v155
	v_pk_add_f32 v[148:149], v[148:149], s[36:37]
	v_pk_add_f32 v[150:151], v[150:151], s[36:37]
	v_pk_add_f32 v[152:153], v[152:153], s[36:37]
	v_pk_add_f32 v[154:155], v[154:155], s[36:37]
	v_rcp_f32_e32 v148, v148
	v_rcp_f32_e32 v150, v150
	v_rcp_f32_e32 v152, v152
	v_rcp_f32_e32 v154, v154
	v_rcp_f32_e32 v149, v149
	v_rcp_f32_e32 v151, v151
	v_rcp_f32_e32 v153, v153
	v_rcp_f32_e32 v155, v155
	v_pk_mul_f32 v[148:149], v[148:149], s[86:87]
	v_pk_mul_f32 v[150:151], v[150:151], s[86:87]
	v_pk_mul_f32 v[152:153], v[152:153], s[86:87]
	v_pk_mul_f32 v[154:155], v[154:155], s[86:87]
	s_nop 0
	v_cvt_pk_f16_f32 v156, v148, v149
	v_cvt_pk_f16_f32 v157, v150, v151
	v_cvt_pk_f16_f32 v158, v152, v153
	v_cvt_pk_f16_f32 v159, v154, v155
	v_lshl_add_u64 v[164:165], v[166:167], 0, s[0:1]
	global_store_dwordx4 v[166:167], v[156:159], off
	v_pk_add_f32 v[36:37], v[36:37], v[140:141]
	v_pk_add_f32 v[38:39], v[38:39], v[142:143]
	v_pk_add_f32 v[32:33], v[32:33], v[144:145]
	v_pk_add_f32 v[34:35], v[34:35], v[146:147]
	v_pk_mul_f32 v[148:149], v[36:37], s[34:35]
	v_pk_mul_f32 v[150:151], v[38:39], s[34:35]
	v_pk_mul_f32 v[152:153], v[32:33], s[34:35]
	v_pk_mul_f32 v[154:155], v[34:35], s[34:35]
	v_exp_f32_e32 v148, v148
	v_exp_f32_e32 v150, v150
	v_exp_f32_e32 v152, v152
	v_exp_f32_e32 v154, v154
	v_exp_f32_e32 v149, v149
; __device__ __forceinline__ u32x4 pack8(f32x4 a, f32x4 b) { u32x4 w; w.x = pk2(a[0], a[1]); w.y = pk2(a[2], a[3]); w.z = pk2(b[0], b[1]); w.w = pk2(b[2], b[3]); return w; }
; __device__ __forceinline__ float sigmoidf_(float x) { return __builtin_amdgcn_rcpf(1.0f + __expf(-x)); }
;     __device__ __forceinline__ void operator()(const f32x4 (&acc)[2][2][4][2], const Unit& u, int wr, int wc, int fr, int fq) const {
;     ...
;                     } else if (mode == E_LORA2) {
;                         const int grp = u.pn >> 2, c = col & 1023;
;                         const size_t off = (size_t)rowg * 1024 + c;
;                         if (grp == 0) {
;                             const f32x4 ba = *(const f32x4*)(bias0 + c), bb = *(const f32x4*)(bias0 + c + 4);
; #pragma unroll
;                             for (int jj = 0; jj < 4; ++jj) { v0[jj] = sigmoidf_(v0[jj] + ba[jj]) * 0.6065306597f; v1[jj] = sigmoidf_(v1[jj] + bb[jj]) * 0.6065306597f; }
;                             *(u32x4*)((h16*)out + off) = pack8(v0, v1);
;                         } else if (grp == 1) {
;                             const f32x4 ba = *(const f32x4*)(bias1 + c), bb = *(const f32x4*)(bias1 + c + 4);
; #pragma unroll
;                             for (int jj = 0; jj < 4; ++jj) { v0[jj] = sigmoidf_(v0[jj] + ba[jj]); v1[jj] = sigmoidf_(v1[jj] + bb[jj]); }
;                             *(u32x4*)((h16*)out + (size_t)MTOK * 1024 + off) = pack8(v0, v1);
	v_exp_f32_e32 v151, v151
	v_exp_f32_e32 v153, v153
	v_exp_f32_e32 v155, v155
	v_pk_add_f32 v[148:149], v[148:149], s[36:37]
	v_pk_add_f32 v[150:151], v[150:151], s[36:37]
	v_pk_add_f32 v[152:153], v[152:153], s[36:37]
	v_pk_add_f32 v[154:155], v[154:155], s[36:37]
	v_rcp_f32_e32 v148, v148
	v_rcp_f32_e32 v150, v150
	v_rcp_f32_e32 v152, v152
	v_rcp_f32_e32 v154, v154
	v_rcp_f32_e32 v149, v149
	v_rcp_f32_e32 v151, v151
	v_rcp_f32_e32 v153, v153
	v_rcp_f32_e32 v155, v155
	v_pk_mul_f32 v[148:149], v[148:149], s[86:87]
	v_pk_mul_f32 v[150:151], v[150:151], s[86:87]
	v_pk_mul_f32 v[152:153], v[152:153], s[86:87]
	v_pk_mul_f32 v[154:155], v[154:155], s[86:87]
	s_nop 0
	v_cvt_pk_f16_f32 v160, v148, v149
	v_cvt_pk_f16_f32 v161, v150, v151
	v_cvt_pk_f16_f32 v162, v152, v153
	v_cvt_pk_f16_f32 v163, v154, v155
	global_store_dwordx4 v[166:167], v[160:163], off offset:256
	v_pk_add_f32 v[28:29], v[28:29], v[132:133]
	v_pk_add_f32 v[30:31], v[30:31], v[134:135]
	v_pk_add_f32 v[24:25], v[24:25], v[136:137]
	v_pk_add_f32 v[26:27], v[26:27], v[138:139]
	v_pk_mul_f32 v[148:149], v[28:29], s[34:35]
	v_pk_mul_f32 v[150:151], v[30:31], s[34:35]
	v_pk_mul_f32 v[152:153], v[24:25], s[34:35]
	v_pk_mul_f32 v[154:155], v[26:27], s[34:35]
	v_exp_f32_e32 v148, v148
	v_exp_f32_e32 v150, v150
	v_exp_f32_e32 v152, v152
	v_exp_f32_e32 v154, v154
	v_exp_f32_e32 v149, v149
	v_exp_f32_e32 v151, v151
	v_exp_f32_e32 v153, v153
	v_exp_f32_e32 v155, v155
	v_pk_add_f32 v[148:149], v[148:149], s[36:37]
	v_pk_add_f32 v[150:151], v[150:151], s[36:37]
	v_pk_add_f32 v[152:153], v[152:153], s[36:37]
	v_pk_add_f32 v[154:155], v[154:155], s[36:37]
	v_rcp_f32_e32 v148, v148
	v_rcp_f32_e32 v150, v150
	v_rcp_f32_e32 v152, v152
	v_rcp_f32_e32 v154, v154
	v_rcp_f32_e32 v149, v149
	v_rcp_f32_e32 v151, v151
	v_rcp_f32_e32 v153, v153
	v_rcp_f32_e32 v155, v155
	v_pk_mul_f32 v[148:149], v[148:149], s[86:87]
	v_pk_mul_f32 v[150:151], v[150:151], s[86:87]
	v_pk_mul_f32 v[152:153], v[152:153], s[86:87]
	v_pk_mul_f32 v[154:155], v[154:155], s[86:87]
	s_nop 0
	v_cvt_pk_f16_f32 v156, v148, v149
	v_cvt_pk_f16_f32 v157, v150, v151
	v_cvt_pk_f16_f32 v158, v152, v153
	v_cvt_pk_f16_f32 v159, v154, v155
	v_lshl_add_u64 v[166:167], v[164:165], 0, s[0:1]
	global_store_dwordx4 v[164:165], v[156:159], off
	v_pk_add_f32 v[20:21], v[20:21], v[140:141]
	v_pk_add_f32 v[22:23], v[22:23], v[142:143]
	v_pk_add_f32 v[16:17], v[16:17], v[144:145]
	v_pk_add_f32 v[18:19], v[18:19], v[146:147]
	v_pk_mul_f32 v[148:149], v[20:21], s[34:35]
	v_pk_mul_f32 v[150:151], v[22:23], s[34:35]
	v_pk_mul_f32 v[152:153], v[16:17], s[34:35]
	v_pk_mul_f32 v[154:155], v[18:19], s[34:35]
	v_exp_f32_e32 v148, v148
	v_exp_f32_e32 v150, v150
	v_exp_f32_e32 v152, v152
	v_exp_f32_e32 v154, v154
	v_exp_f32_e32 v149, v149
	v_exp_f32_e32 v151, v151
	v_exp_f32_e32 v153, v153
	v_exp_f32_e32 v155, v155
	v_pk_add_f32 v[148:149], v[148:149], s[36:37]
	v_pk_add_f32 v[150:151], v[150:151], s[36:37]
	v_pk_add_f32 v[152:153], v[152:153], s[36:37]
	v_pk_add_f32 v[154:155], v[154:155], s[36:37]
	v_rcp_f32_e32 v148, v148
	v_rcp_f32_e32 v150, v150
	v_rcp_f32_e32 v152, v152
	v_rcp_f32_e32 v154, v154
	v_rcp_f32_e32 v149, v149
	v_rcp_f32_e32 v151, v151
	v_rcp_f32_e32 v153, v153
	v_rcp_f32_e32 v155, v155
	v_pk_mul_f32 v[148:149], v[148:149], s[86:87]
	v_pk_mul_f32 v[150:151], v[150:151], s[86:87]
	v_pk_mul_f32 v[152:153], v[152:153], s[86:87]
	v_pk_mul_f32 v[154:155], v[154:155], s[86:87]
	s_nop 0
	v_cvt_pk_f16_f32 v160, v148, v149
	v_cvt_pk_f16_f32 v161, v150, v151
	v_cvt_pk_f16_f32 v162, v152, v153
	v_cvt_pk_f16_f32 v163, v154, v155
	global_store_dwordx4 v[164:165], v[160:163], off offset:256
	v_pk_add_f32 v[12:13], v[12:13], v[132:133]
	v_pk_add_f32 v[14:15], v[14:15], v[134:135]
	v_pk_add_f32 v[8:9], v[8:9], v[136:137]
	v_pk_add_f32 v[10:11], v[10:11], v[138:139]
	v_pk_mul_f32 v[148:149], v[12:13], s[34:35]
	v_pk_mul_f32 v[150:151], v[14:15], s[34:35]
	v_pk_mul_f32 v[152:153], v[8:9], s[34:35]
	v_pk_mul_f32 v[154:155], v[10:11], s[34:35]
	v_exp_f32_e32 v148, v148
	v_exp_f32_e32 v150, v150
	v_exp_f32_e32 v152, v152
	v_exp_f32_e32 v154, v154
	v_exp_f32_e32 v149, v149
	v_exp_f32_e32 v151, v151
	v_exp_f32_e32 v153, v153
	v_exp_f32_e32 v155, v155
	v_pk_add_f32 v[148:149], v[148:149], s[36:37]
	v_pk_add_f32 v[150:151], v[150:151], s[36:37]
	v_pk_add_f32 v[152:153], v[152:153], s[36:37]
	v_pk_add_f32 v[154:155], v[154:155], s[36:37]
	v_rcp_f32_e32 v148, v148
	v_rcp_f32_e32 v150, v150
	v_rcp_f32_e32 v152, v152
	v_rcp_f32_e32 v154, v154
	v_rcp_f32_e32 v149, v149
	v_rcp_f32_e32 v151, v151
	v_rcp_f32_e32 v153, v153
	v_rcp_f32_e32 v155, v155
	v_pk_mul_f32 v[148:149], v[148:149], s[86:87]
	v_pk_mul_f32 v[150:151], v[150:151], s[86:87]
	v_pk_mul_f32 v[152:153], v[152:153], s[86:87]
	v_pk_mul_f32 v[154:155], v[154:155], s[86:87]
	s_nop 0
	v_cvt_pk_f16_f32 v156, v148, v149
	v_cvt_pk_f16_f32 v157, v150, v151
	v_cvt_pk_f16_f32 v158, v152, v153
	v_cvt_pk_f16_f32 v159, v154, v155
	global_store_dwordx4 v[166:167], v[156:159], off
	v_pk_add_f32 v[4:5], v[4:5], v[140:141]
	v_pk_add_f32 v[6:7], v[6:7], v[142:143]
	v_pk_add_f32 v[0:1], v[0:1], v[144:145]
	v_pk_add_f32 v[2:3], v[2:3], v[146:147]
	v_pk_mul_f32 v[148:149], v[4:5], s[34:35]
	v_pk_mul_f32 v[150:151], v[6:7], s[34:35]
	v_pk_mul_f32 v[152:153], v[0:1], s[34:35]
	v_pk_mul_f32 v[154:155], v[2:3], s[34:35]
	v_exp_f32_e32 v148, v148
	v_exp_f32_e32 v150, v150
	v_exp_f32_e32 v152, v152
	v_exp_f32_e32 v154, v154
	v_exp_f32_e32 v149, v149
	v_exp_f32_e32 v151, v151
	v_exp_f32_e32 v153, v153
	v_exp_f32_e32 v155, v155
	v_pk_add_f32 v[148:149], v[148:149], s[36:37]
	v_pk_add_f32 v[150:151], v[150:151], s[36:37]
	v_pk_add_f32 v[152:153], v[152:153], s[36:37]
	v_pk_add_f32 v[154:155], v[154:155], s[36:37]
	v_rcp_f32_e32 v148, v148
	v_rcp_f32_e32 v150, v150
	v_rcp_f32_e32 v152, v152
	v_rcp_f32_e32 v154, v154
	v_rcp_f32_e32 v149, v149
	v_rcp_f32_e32 v151, v151
	v_rcp_f32_e32 v153, v153
	v_rcp_f32_e32 v155, v155
	v_pk_mul_f32 v[148:149], v[148:149], s[86:87]
	v_pk_mul_f32 v[150:151], v[150:151], s[86:87]
	v_pk_mul_f32 v[152:153], v[152:153], s[86:87]
	v_pk_mul_f32 v[154:155], v[154:155], s[86:87]
	s_nop 0
	v_cvt_pk_f16_f32 v160, v148, v149
	v_cvt_pk_f16_f32 v161, v150, v151
	v_cvt_pk_f16_f32 v162, v152, v153
	v_cvt_pk_f16_f32 v163, v154, v155
	global_store_dwordx4 v[166:167], v[160:163], off offset:256
	s_branch .LBB0_740

; #define PG8_STAGE(bufoff, gbase, voff) do { _Pragma("unroll") for (int _i = 0; _i < 2; ++_i) \
;         __builtin_amdgcn_global_load_lds((const unsigned*)((const char*)(gbase) + (voff)[_i]), (LAS unsigned*)(lds + (bufoff) + ldsw + _i * 8192), 16, 0, 0); } while (0)
; #define PG8_LDA(dst, b, h) do { _Pragma("unroll") for (int m = 0; m < 4; ++m) _Pragma("unroll") for (int k = 0; k < 2; ++k) dst[m][k] = *(const LAS h16x8*)(lds + PG8_SA(b, h) + aoff + m * 2048 + k * 1024); } while (0)
; #define PG8_LDB(dst, b, h) do { _Pragma("unroll") for (int n = 0; n < 2; ++n) _Pragma("unroll") for (int k = 0; k < 2; ++k) dst[n][k] = *(const LAS h16x8*)(lds + PG8_SB(b, h) + boff + n * 2048 + k * 1024); } while (0)
; #define PG8_MMA(ai, bj, At, Bt) do { __builtin_amdgcn_s_setprio(1); _Pragma("unroll") for (int m = 0; m < 4; ++m) _Pragma("unroll") for (int n = 0; n < 2; ++n) _Pragma("unroll") for (int k = 0; k < 2; ++k) \
;         acc[ai][bj][m][n] = __builtin_amdgcn_mfma_f32_16x16x32_f16(Bt[n][k], At[m][k], acc[ai][bj][m][n], 0, 0, 0); __builtin_amdgcn_s_setprio(0); } while (0)
; #define PG8_WAIT_V(n) asm volatile("s_waitcnt vmcnt(" #n ")" ::: "memory")
; #define PG8_WAIT_L(n) asm volatile("s_waitcnt lgkmcnt(" #n ")" ::: "memory")
; #define PG8_BAR __builtin_amdgcn_s_barrier()
; #define PG8_SCHED __builtin_amdgcn_sched_barrier(0)
; __device__ __forceinline__ void gemm_phase(LAS unsigned char* lds, const Gemm g, const StaticOrder& S, const Epi& E) {
;     ...
;             PG8_LDB(B0, 0, 0); PG8_SCHED; PG8_LDA(At, 0, 0); PG8_STAGE(PG8_SA(1, 1), a1 + hstepA, voffA);
;             PG8_WAIT_L(8); PG8_BAR; PG8_WAIT_L(0); PG8_MMA(0, 0, At, B0); PG8_BAR; PG8_SCHED;
;             PG8_LDB(B1, 0, 1); PG8_STAGE(PG8_SB(0, 0), b2, voffB);
;             PG8_BAR; PG8_WAIT_L(0); PG8_MMA(0, 1, At, B1); PG8_BAR;
;             PG8_LDA(At, 0, 1); PG8_STAGE(PG8_SA(0, 0), a2, voffA);
;             PG8_BAR; PG8_WAIT_L(0); PG8_MMA(1, 0, At, B0); PG8_BAR; PG8_SCHED;
;             PG8_STAGE(PG8_SB(0, 1), b2 + hstepB, voffB);
;             PG8_WAIT_V(6); PG8_BAR; PG8_MMA(1, 1, At, B1); PG8_BAR;
.LBB0_762:
	s_cmp_gt_u32 s34, 15
	s_cselect_b64 s[36:37], -1, 0
	s_and_b64 s[36:37], s[6:7], s[36:37]
	s_and_b64 s[36:37], s[36:37], exec
	s_cselect_b32 s42, 0xfffff000, 0
	s_cselect_b32 s43, -1, 0
	s_add_i32 s38, s34, 2
	s_cmp_gt_u32 s34, 13
	s_cselect_b64 s[36:37], -1, 0
	s_and_b64 s[36:37], s[6:7], s[36:37]
	s_and_b64 s[36:37], s[36:37], exec
	s_cselect_b32 s36, 0xfffff000, 0
	s_cselect_b32 s35, -1, 0
	s_add_u32 s36, s0, s36
	s_addc_u32 s35, s1, s35
	s_add_u32 s36, s36, 0x80
	s_addc_u32 s35, s35, 0
	s_add_i32 s39, 0, 0x10000
	v_add_u32_e32 v140, s39, v238
	ds_read_b128 v[128:131], v140
	ds_read_b128 v[132:135], v140 offset:1024
	ds_read_b128 v[136:139], v140 offset:2048
	ds_read_b128 v[140:143], v140 offset:3072
	s_cmp_eq_u32 s66, s34
	s_cselect_b32 s34, s4, s36
	s_cselect_b32 s35, s5, s35
	s_cselect_b32 s37, s29, s33
	s_cselect_b32 s36, s28, s27
	v_lshl_add_u64 v[176:177], s[0:1], 0, v[212:213]
	v_lshl_add_u64 v[176:177], v[176:177], 0, s[42:43]
	s_add_i32 m0, s58, 0xc000
	ds_read_b128 v[144:147], v239
	ds_read_b128 v[148:151], v239 offset:1024
	ds_read_b128 v[152:155], v239 offset:2048
	ds_read_b128 v[156:159], v239 offset:3072
	ds_read_b128 v[160:163], v239 offset:4096
	ds_read_b128 v[164:167], v239 offset:5120
	ds_read_b128 v[168:171], v239 offset:6144
	ds_read_b128 v[172:175], v239 offset:7168
	global_load_lds_dwordx4 v[176:177], off
	v_lshl_add_u64 v[176:177], s[0:1], 0, v[214:215]
	v_lshl_add_u64 v[176:177], v[176:177], 0, s[42:43]
	s_add_i32 m0, s58, 0xe000
	s_nop 0
	global_load_lds_dwordx4 v[176:177], off
	s_waitcnt lgkmcnt(8)
	s_barrier
	s_waitcnt lgkmcnt(0)
	s_setprio 1
	s_waitcnt lgkmcnt(0)
	v_mfma_f32_16x16x32_f16 v[124:127], v[128:131], v[144:147], v[124:127]
	v_mfma_f32_16x16x32_f16 v[120:123], v[136:139], v[144:147], v[120:123]
	v_mfma_f32_16x16x32_f16 v[108:111], v[128:131], v[152:155], v[108:111]
	v_mfma_f32_16x16x32_f16 v[104:107], v[136:139], v[152:155], v[104:107]
	v_mfma_f32_16x16x32_f16 v[92:95], v[128:131], v[160:163], v[92:95]
	v_mfma_f32_16x16x32_f16 v[88:91], v[136:139], v[160:163], v[88:91]
	v_mfma_f32_16x16x32_f16 v[76:79], v[128:131], v[168:171], v[76:79]
	v_mfma_f32_16x16x32_f16 v[72:75], v[136:139], v[168:171], v[72:75]
	v_mfma_f32_16x16x32_f16 v[124:127], v[132:135], v[148:151], v[124:127]
	v_mfma_f32_16x16x32_f16 v[120:123], v[140:143], v[148:151], v[120:123]
	v_mfma_f32_16x16x32_f16 v[108:111], v[132:135], v[156:159], v[108:111]
	v_mfma_f32_16x16x32_f16 v[104:107], v[140:143], v[156:159], v[104:107]
	v_mfma_f32_16x16x32_f16 v[92:95], v[132:135], v[164:167], v[92:95]
	v_mfma_f32_16x16x32_f16 v[88:91], v[140:143], v[164:167], v[88:91]
	v_mfma_f32_16x16x32_f16 v[76:79], v[132:135], v[172:175], v[76:79]
	v_mfma_f32_16x16x32_f16 v[72:75], v[140:143], v[172:175], v[72:75]
	s_setprio 0
	s_barrier
	s_add_i32 s42, 0, 0x14000
	s_add_i32 s39, s39, s31
	v_add_u32_e32 v188, s42, v238
	v_lshl_add_u64 v[192:193], s[36:37], 0, v[206:207]
	s_mov_b32 m0, s39
	ds_read_b128 v[176:179], v188
	ds_read_b128 v[180:183], v188 offset:1024
	ds_read_b128 v[184:187], v188 offset:2048
	ds_read_b128 v[188:191], v188 offset:3072
	global_load_lds_dwordx4 v[192:193], off
	v_lshl_add_u64 v[194:195], s[36:37], 0, v[210:211]
	s_add_i32 m0, s39, 0x2000
	s_nop 0
	global_load_lds_dwordx4 v[194:195], off
	s_barrier
	s_waitcnt lgkmcnt(0)
	s_setprio 1
	s_waitcnt lgkmcnt(0)
	v_mfma_f32_16x16x32_f16 v[116:119], v[176:179], v[144:147], v[116:119]
	v_mfma_f32_16x16x32_f16 v[112:115], v[184:187], v[144:147], v[112:115]
	v_mfma_f32_16x16x32_f16 v[100:103], v[176:179], v[152:155], v[100:103]
	v_mfma_f32_16x16x32_f16 v[96:99], v[184:187], v[152:155], v[96:99]
	v_mfma_f32_16x16x32_f16 v[84:87], v[176:179], v[160:163], v[84:87]
	v_mfma_f32_16x16x32_f16 v[80:83], v[184:187], v[160:163], v[80:83]
	v_mfma_f32_16x16x32_f16 v[68:71], v[176:179], v[168:171], v[68:71]
	v_mfma_f32_16x16x32_f16 v[64:67], v[184:187], v[168:171], v[64:67]
	v_mfma_f32_16x16x32_f16 v[116:119], v[180:183], v[148:151], v[116:119]
	v_mfma_f32_16x16x32_f16 v[112:115], v[188:191], v[148:151], v[112:115]
	v_mfma_f32_16x16x32_f16 v[100:103], v[180:183], v[156:159], v[100:103]
	v_mfma_f32_16x16x32_f16 v[96:99], v[188:191], v[156:159], v[96:99]
	v_mfma_f32_16x16x32_f16 v[84:87], v[180:183], v[164:167], v[84:87]
	v_mfma_f32_16x16x32_f16 v[80:83], v[188:191], v[164:167], v[80:83]
	v_mfma_f32_16x16x32_f16 v[68:71], v[180:183], v[172:175], v[68:71]
	v_mfma_f32_16x16x32_f16 v[64:67], v[188:191], v[172:175], v[64:67]
	s_setprio 0
	s_mov_b32 m0, s58
	v_lshl_add_u64 v[216:217], s[34:35], 0, v[204:205]
	s_barrier
	ds_read_b128 v[144:147], v239 offset:16384
	ds_read_b128 v[148:151], v239 offset:17408
	ds_read_b128 v[152:155], v239 offset:18432
	ds_read_b128 v[156:159], v239 offset:19456
	ds_read_b128 v[160:163], v239 offset:20480
	ds_read_b128 v[164:167], v239 offset:21504
	ds_read_b128 v[168:171], v239 offset:22528
	ds_read_b128 v[172:175], v239 offset:23552
	global_load_lds_dwordx4 v[216:217], off
	v_lshl_add_u64 v[218:219], s[34:35], 0, v[208:209]
	s_mov_b32 m0, s59
	s_nop 0
	global_load_lds_dwordx4 v[218:219], off
	s_barrier
; #define PG8_STAGE(bufoff, gbase, voff) do { _Pragma("unroll") for (int _i = 0; _i < 2; ++_i) \
;         __builtin_amdgcn_global_load_lds((const unsigned*)((const char*)(gbase) + (voff)[_i]), (LAS unsigned*)(lds + (bufoff) + ldsw + _i * 8192), 16, 0, 0); } while (0)
; #define PG8_LDA(dst, b, h) do { _Pragma("unroll") for (int m = 0; m < 4; ++m) _Pragma("unroll") for (int k = 0; k < 2; ++k) dst[m][k] = *(const LAS h16x8*)(lds + PG8_SA(b, h) + aoff + m * 2048 + k * 1024); } while (0)
; #define PG8_LDB(dst, b, h) do { _Pragma("unroll") for (int n = 0; n < 2; ++n) _Pragma("unroll") for (int k = 0; k < 2; ++k) dst[n][k] = *(const LAS h16x8*)(lds + PG8_SB(b, h) + boff + n * 2048 + k * 1024); } while (0)
; #define PG8_MMA(ai, bj, At, Bt) do { __builtin_amdgcn_s_setprio(1); _Pragma("unroll") for (int m = 0; m < 4; ++m) _Pragma("unroll") for (int n = 0; n < 2; ++n) _Pragma("unroll") for (int k = 0; k < 2; ++k) \
;         acc[ai][bj][m][n] = __builtin_amdgcn_mfma_f32_16x16x32_f16(Bt[n][k], At[m][k], acc[ai][bj][m][n], 0, 0, 0); __builtin_amdgcn_s_setprio(0); } while (0)
; #define PG8_WAIT_V(n) asm volatile("s_waitcnt vmcnt(" #n ")" ::: "memory")
; #define PG8_WAIT_L(n) asm volatile("s_waitcnt lgkmcnt(" #n ")" ::: "memory")
; #define PG8_BAR __builtin_amdgcn_s_barrier()
; #define PG8_SCHED __builtin_amdgcn_sched_barrier(0)
; __device__ __forceinline__ void gemm_phase(LAS unsigned char* lds, const Gemm g, const StaticOrder& S, const Epi& E) {
;     ...
;             PG8_WAIT_V(6); PG8_BAR; PG8_MMA(1, 1, At, B1); PG8_BAR;
;             PG8_LDB(B0, 1, 0); PG8_SCHED; PG8_LDA(At, 1, 0); PG8_STAGE(PG8_SA(0, 1), a2 + hstepA, voffA);
;             PG8_WAIT_L(8); PG8_BAR; PG8_WAIT_L(0); PG8_MMA(0, 0, At, B0); PG8_BAR; PG8_SCHED;
;             PG8_LDB(B1, 1, 1); PG8_STAGE(PG8_SB(1, 0), b3, voffB);
;             PG8_BAR; PG8_WAIT_L(0); PG8_MMA(0, 1, At, B1); PG8_BAR;
;             PG8_LDA(At, 1, 1); PG8_STAGE(PG8_SA(1, 0), a3, voffA);
	s_waitcnt lgkmcnt(0)
	s_setprio 1
	s_waitcnt lgkmcnt(0)
	v_mfma_f32_16x16x32_f16 v[60:63], v[128:131], v[144:147], v[60:63]
	v_mfma_f32_16x16x32_f16 v[56:59], v[136:139], v[144:147], v[56:59]
	v_mfma_f32_16x16x32_f16 v[44:47], v[128:131], v[152:155], v[44:47]
	v_mfma_f32_16x16x32_f16 v[40:43], v[136:139], v[152:155], v[40:43]
	v_mfma_f32_16x16x32_f16 v[28:31], v[128:131], v[160:163], v[28:31]
	v_mfma_f32_16x16x32_f16 v[24:27], v[136:139], v[160:163], v[24:27]
	v_mfma_f32_16x16x32_f16 v[12:15], v[128:131], v[168:171], v[12:15]
	v_mfma_f32_16x16x32_f16 v[8:11], v[136:139], v[168:171], v[8:11]
	v_mfma_f32_16x16x32_f16 v[60:63], v[132:135], v[148:151], v[60:63]
	v_mfma_f32_16x16x32_f16 v[56:59], v[140:143], v[148:151], v[56:59]
	v_mfma_f32_16x16x32_f16 v[44:47], v[132:135], v[156:159], v[44:47]
	v_mfma_f32_16x16x32_f16 v[40:43], v[140:143], v[156:159], v[40:43]
	v_mfma_f32_16x16x32_f16 v[28:31], v[132:135], v[164:167], v[28:31]
	v_mfma_f32_16x16x32_f16 v[24:27], v[140:143], v[164:167], v[24:27]
	v_mfma_f32_16x16x32_f16 v[12:15], v[132:135], v[172:175], v[12:15]
	v_mfma_f32_16x16x32_f16 v[8:11], v[140:143], v[172:175], v[8:11]
	s_setprio 0
	s_barrier
	s_add_u32 s36, s36, s18
	s_addc_u32 s37, s37, s19
	s_add_i32 s39, s42, s31
	v_lshl_add_u64 v[220:221], s[36:37], 0, v[206:207]
	s_mov_b32 m0, s39
	v_lshl_add_u64 v[222:223], s[36:37], 0, v[210:211]
	global_load_lds_dwordx4 v[220:221], off
	s_add_i32 m0, s39, 0x2000
	s_nop 0
	global_load_lds_dwordx4 v[222:223], off
	s_waitcnt vmcnt(6)
	s_barrier
	s_setprio 1
	v_mfma_f32_16x16x32_f16 v[52:55], v[176:179], v[144:147], v[52:55]
	v_mfma_f32_16x16x32_f16 v[48:51], v[184:187], v[144:147], v[48:51]
	v_mfma_f32_16x16x32_f16 v[36:39], v[176:179], v[152:155], v[36:39]
	v_mfma_f32_16x16x32_f16 v[32:35], v[184:187], v[152:155], v[32:35]
	v_mfma_f32_16x16x32_f16 v[20:23], v[176:179], v[160:163], v[20:23]
	v_mfma_f32_16x16x32_f16 v[16:19], v[184:187], v[160:163], v[16:19]
	v_mfma_f32_16x16x32_f16 v[4:7], v[176:179], v[168:171], v[4:7]
	v_mfma_f32_16x16x32_f16 v[0:3], v[184:187], v[168:171], v[0:3]
	v_mfma_f32_16x16x32_f16 v[52:55], v[180:183], v[148:151], v[52:55]
	v_mfma_f32_16x16x32_f16 v[48:51], v[188:191], v[148:151], v[48:51]
	v_mfma_f32_16x16x32_f16 v[36:39], v[180:183], v[156:159], v[36:39]
	v_mfma_f32_16x16x32_f16 v[32:35], v[188:191], v[156:159], v[32:35]
	v_mfma_f32_16x16x32_f16 v[20:23], v[180:183], v[164:167], v[20:23]
	v_mfma_f32_16x16x32_f16 v[16:19], v[188:191], v[164:167], v[16:19]
	v_mfma_f32_16x16x32_f16 v[4:7], v[180:183], v[172:175], v[4:7]
	v_mfma_f32_16x16x32_f16 v[0:3], v[188:191], v[172:175], v[0:3]
	s_setprio 0
	s_add_i32 s36, 0, 0x18000
	v_add_u32_e32 v140, s36, v238
	s_barrier
	ds_read_b128 v[128:131], v140
	ds_read_b128 v[132:135], v140 offset:1024
	ds_read_b128 v[136:139], v140 offset:2048
	ds_read_b128 v[140:143], v140 offset:3072
	s_add_u32 s34, s34, s16
	s_addc_u32 s35, s35, s17
	s_mov_b32 m0, s60
	v_lshl_add_u64 v[176:177], s[34:35], 0, v[204:205]
	ds_read_b128 v[144:147], v239 offset:32768
	ds_read_b128 v[148:151], v239 offset:33792
	ds_read_b128 v[152:155], v239 offset:34816
	ds_read_b128 v[156:159], v239 offset:35840
	ds_read_b128 v[160:163], v239 offset:36864
	ds_read_b128 v[164:167], v239 offset:37888
	ds_read_b128 v[168:171], v239 offset:38912
	ds_read_b128 v[172:175], v239 offset:39936
	global_load_lds_dwordx4 v[176:177], off
	v_lshl_add_u64 v[176:177], s[34:35], 0, v[208:209]
	s_mov_b32 m0, s61
	s_nop 0
	global_load_lds_dwordx4 v[176:177], off
	s_waitcnt lgkmcnt(8)
	s_barrier
	s_waitcnt lgkmcnt(0)
	s_setprio 1
	s_waitcnt lgkmcnt(0)
	v_mfma_f32_16x16x32_f16 v[124:127], v[128:131], v[144:147], v[124:127]
	v_mfma_f32_16x16x32_f16 v[120:123], v[136:139], v[144:147], v[120:123]
	v_mfma_f32_16x16x32_f16 v[108:111], v[128:131], v[152:155], v[108:111]
	v_mfma_f32_16x16x32_f16 v[104:107], v[136:139], v[152:155], v[104:107]
	v_mfma_f32_16x16x32_f16 v[92:95], v[128:131], v[160:163], v[92:95]
	v_mfma_f32_16x16x32_f16 v[88:91], v[136:139], v[160:163], v[88:91]
	v_mfma_f32_16x16x32_f16 v[76:79], v[128:131], v[168:171], v[76:79]
	v_mfma_f32_16x16x32_f16 v[72:75], v[136:139], v[168:171], v[72:75]
	v_mfma_f32_16x16x32_f16 v[124:127], v[132:135], v[148:151], v[124:127]
	v_mfma_f32_16x16x32_f16 v[120:123], v[140:143], v[148:151], v[120:123]
	v_mfma_f32_16x16x32_f16 v[108:111], v[132:135], v[156:159], v[108:111]
	v_mfma_f32_16x16x32_f16 v[104:107], v[140:143], v[156:159], v[104:107]
	v_mfma_f32_16x16x32_f16 v[92:95], v[132:135], v[164:167], v[92:95]
	v_mfma_f32_16x16x32_f16 v[88:91], v[140:143], v[164:167], v[88:91]
	v_mfma_f32_16x16x32_f16 v[76:79], v[132:135], v[172:175], v[76:79]
	v_mfma_f32_16x16x32_f16 v[72:75], v[140:143], v[172:175], v[72:75]
	s_setprio 0
	s_barrier
	s_add_i32 s34, 0, 0x1c000
	s_add_i32 s35, s36, s31
	v_add_u32_e32 v188, s34, v238
	v_lshl_add_u64 v[192:193], v[192:193], 0, s[80:81]
	s_mov_b32 m0, s35
	ds_read_b128 v[176:179], v188
	ds_read_b128 v[180:183], v188 offset:1024
	ds_read_b128 v[184:187], v188 offset:2048
	ds_read_b128 v[188:191], v188 offset:3072
	global_load_lds_dwordx4 v[192:193], off
	v_lshl_add_u64 v[192:193], v[194:195], 0, s[80:81]
	s_add_i32 m0, s35, 0x2000
	s_nop 0
	global_load_lds_dwordx4 v[192:193], off
	s_barrier
; __device__ __forceinline__ u32x4 pack8(f32x4 a, f32x4 b) { u32x4 w; w.x = pk2(a[0], a[1]); w.y = pk2(a[2], a[3]); w.z = pk2(b[0], b[1]); w.w = pk2(b[2], b[3]); return w; }
; __device__ __forceinline__ float sigmoidf_(float x) { return __builtin_amdgcn_rcpf(1.0f + __expf(-x)); }
; #define PG8_STAGE(bufoff, gbase, voff) do { _Pragma("unroll") for (int _i = 0; _i < 2; ++_i) \
;         __builtin_amdgcn_global_load_lds((const unsigned*)((const char*)(gbase) + (voff)[_i]), (LAS unsigned*)(lds + (bufoff) + ldsw + _i * 8192), 16, 0, 0); } while (0)
; #define PG8_LDA(dst, b, h) do { _Pragma("unroll") for (int m = 0; m < 4; ++m) _Pragma("unroll") for (int k = 0; k < 2; ++k) dst[m][k] = *(const LAS h16x8*)(lds + PG8_SA(b, h) + aoff + m * 2048 + k * 1024); } while (0)
;     __device__ __forceinline__ void operator()(const f32x4 (&acc)[2][2][4][2], const Unit& u, int wr, int wc, int fr, int fq) const {
;     ...
;                     } else if (mode == E_LORA2) {
;                         const int grp = u.pn >> 2, c = col & 1023;
;                         const size_t off = (size_t)rowg * 1024 + c;
;                         if (grp == 0) {
;                             const f32x4 ba = *(const f32x4*)(bias0 + c), bb = *(const f32x4*)(bias0 + c + 4);
; #pragma unroll
;                             for (int jj = 0; jj < 4; ++jj) { v0[jj] = sigmoidf_(v0[jj] + ba[jj]) * 0.6065306597f; v1[jj] = sigmoidf_(v1[jj] + bb[jj]) * 0.6065306597f; }
;                             *(u32x4*)((h16*)out + off) = pack8(v0, v1);
;                         } else if (grp == 1) {
;                             const f32x4 ba = *(const f32x4*)(bias1 + c), bb = *(const f32x4*)(bias1 + c + 4);
; #pragma unroll
;                             for (int jj = 0; jj < 4; ++jj) { v0[jj] = sigmoidf_(v0[jj] + ba[jj]); v1[jj] = sigmoidf_(v1[jj] + bb[jj]); }
;                             *(u32x4*)((h16*)out + (size_t)MTOK * 1024 + off) = pack8(v0, v1);
; __device__ __forceinline__ void gemm_phase(LAS unsigned char* lds, const Gemm g, const StaticOrder& S, const Epi& E) {
;     ...
;             PG8_LDA(At, 1, 1); PG8_STAGE(PG8_SA(1, 0), a3, voffA);
;             PG8_BAR; PG8_WAIT_L(0); PG8_MMA(1, 0, At, B0); PG8_BAR; PG8_SCHED;
;             PG8_STAGE(PG8_SB(1, 1), b3 + hstepB, voffB);
;             PG8_WAIT_V(6); PG8_BAR; PG8_MMA(1, 1, At, B1); PG8_BAR;
;         }
;         E(acc, cur, wr, wc, fr, fq);
	s_waitcnt lgkmcnt(0)
	s_setprio 1
	s_waitcnt lgkmcnt(0)
	v_mfma_f32_16x16x32_f16 v[116:119], v[176:179], v[144:147], v[116:119]
	v_mfma_f32_16x16x32_f16 v[112:115], v[184:187], v[144:147], v[112:115]
	v_mfma_f32_16x16x32_f16 v[100:103], v[176:179], v[152:155], v[100:103]
	v_mfma_f32_16x16x32_f16 v[96:99], v[184:187], v[152:155], v[96:99]
	v_mfma_f32_16x16x32_f16 v[84:87], v[176:179], v[160:163], v[84:87]
	v_mfma_f32_16x16x32_f16 v[80:83], v[184:187], v[160:163], v[80:83]
	v_mfma_f32_16x16x32_f16 v[68:71], v[176:179], v[168:171], v[68:71]
	v_mfma_f32_16x16x32_f16 v[64:67], v[184:187], v[168:171], v[64:67]
	v_mfma_f32_16x16x32_f16 v[116:119], v[180:183], v[148:151], v[116:119]
	v_mfma_f32_16x16x32_f16 v[112:115], v[188:191], v[148:151], v[112:115]
	v_mfma_f32_16x16x32_f16 v[100:103], v[180:183], v[156:159], v[100:103]
	v_mfma_f32_16x16x32_f16 v[96:99], v[188:191], v[156:159], v[96:99]
	v_mfma_f32_16x16x32_f16 v[84:87], v[180:183], v[164:167], v[84:87]
	v_mfma_f32_16x16x32_f16 v[80:83], v[188:191], v[164:167], v[80:83]
	v_mfma_f32_16x16x32_f16 v[68:71], v[180:183], v[172:175], v[68:71]
	v_mfma_f32_16x16x32_f16 v[64:67], v[188:191], v[172:175], v[64:67]
	s_setprio 0
	s_mov_b32 m0, s62
	v_lshl_add_u64 v[192:193], v[216:217], 0, s[80:81]
	s_barrier
	ds_read_b128 v[144:147], v239 offset:49152
	ds_read_b128 v[148:151], v239 offset:50176
	ds_read_b128 v[152:155], v239 offset:51200
	ds_read_b128 v[156:159], v239 offset:52224
	ds_read_b128 v[160:163], v239 offset:53248
	ds_read_b128 v[164:167], v239 offset:54272
	ds_read_b128 v[168:171], v239 offset:55296
	ds_read_b128 v[172:175], v239 offset:56320
	global_load_lds_dwordx4 v[192:193], off
	v_lshl_add_u64 v[192:193], v[218:219], 0, s[80:81]
	s_mov_b32 m0, s63
	s_nop 0
	global_load_lds_dwordx4 v[192:193], off
	s_barrier
	s_waitcnt lgkmcnt(0)
	s_setprio 1
	s_waitcnt lgkmcnt(0)
	v_mfma_f32_16x16x32_f16 v[60:63], v[128:131], v[144:147], v[60:63]
	v_mfma_f32_16x16x32_f16 v[56:59], v[136:139], v[144:147], v[56:59]
	v_mfma_f32_16x16x32_f16 v[44:47], v[128:131], v[152:155], v[44:47]
	v_mfma_f32_16x16x32_f16 v[40:43], v[136:139], v[152:155], v[40:43]
	v_mfma_f32_16x16x32_f16 v[28:31], v[128:131], v[160:163], v[28:31]
	v_mfma_f32_16x16x32_f16 v[24:27], v[136:139], v[160:163], v[24:27]
	v_mfma_f32_16x16x32_f16 v[12:15], v[128:131], v[168:171], v[12:15]
	v_mfma_f32_16x16x32_f16 v[8:11], v[136:139], v[168:171], v[8:11]
	v_mfma_f32_16x16x32_f16 v[60:63], v[132:135], v[148:151], v[60:63]
	v_mfma_f32_16x16x32_f16 v[56:59], v[140:143], v[148:151], v[56:59]
	v_mfma_f32_16x16x32_f16 v[44:47], v[132:135], v[156:159], v[44:47]
	v_mfma_f32_16x16x32_f16 v[40:43], v[140:143], v[156:159], v[40:43]
	v_mfma_f32_16x16x32_f16 v[28:31], v[132:135], v[164:167], v[28:31]
	v_mfma_f32_16x16x32_f16 v[24:27], v[140:143], v[164:167], v[24:27]
	v_mfma_f32_16x16x32_f16 v[12:15], v[132:135], v[172:175], v[12:15]
	v_mfma_f32_16x16x32_f16 v[8:11], v[140:143], v[172:175], v[8:11]
	s_setprio 0
	s_barrier
	s_add_i32 s34, s34, s31
	v_lshl_add_u64 v[128:129], v[220:221], 0, s[80:81]
	s_mov_b32 m0, s34
	s_nop 0
	global_load_lds_dwordx4 v[128:129], off
	v_lshl_add_u64 v[128:129], v[222:223], 0, s[80:81]
	s_add_i32 m0, s34, 0x2000
	s_nop 0
	global_load_lds_dwordx4 v[128:129], off
	s_waitcnt vmcnt(6)
	s_barrier
	s_setprio 1
	v_mfma_f32_16x16x32_f16 v[52:55], v[176:179], v[144:147], v[52:55]
	v_mfma_f32_16x16x32_f16 v[48:51], v[184:187], v[144:147], v[48:51]
	v_mfma_f32_16x16x32_f16 v[36:39], v[176:179], v[152:155], v[36:39]
	v_mfma_f32_16x16x32_f16 v[32:35], v[184:187], v[152:155], v[32:35]
	v_mfma_f32_16x16x32_f16 v[20:23], v[176:179], v[160:163], v[20:23]
	v_mfma_f32_16x16x32_f16 v[16:19], v[184:187], v[160:163], v[16:19]
	v_mfma_f32_16x16x32_f16 v[4:7], v[176:179], v[168:171], v[4:7]
	v_mfma_f32_16x16x32_f16 v[0:3], v[184:187], v[168:171], v[0:3]
	v_mfma_f32_16x16x32_f16 v[52:55], v[180:183], v[148:151], v[52:55]
	v_mfma_f32_16x16x32_f16 v[48:51], v[188:191], v[148:151], v[48:51]
	v_mfma_f32_16x16x32_f16 v[36:39], v[180:183], v[156:159], v[36:39]
	v_mfma_f32_16x16x32_f16 v[32:35], v[188:191], v[156:159], v[32:35]
	v_mfma_f32_16x16x32_f16 v[20:23], v[180:183], v[164:167], v[20:23]
	v_mfma_f32_16x16x32_f16 v[16:19], v[188:191], v[164:167], v[16:19]
	v_mfma_f32_16x16x32_f16 v[4:7], v[180:183], v[172:175], v[4:7]
	v_mfma_f32_16x16x32_f16 v[0:3], v[188:191], v[172:175], v[0:3]
	s_setprio 0
	s_add_u32 s0, s0, 0x100
	s_addc_u32 s1, s1, 0
	s_add_u32 s27, s27, 0x100
	s_addc_u32 s33, s33, 0
	s_cmp_ge_u32 s38, s64
	s_mov_b32 s34, s38
	s_barrier
	s_cbranch_scc0 .LBB0_762
	s_lshl_b32 s0, s84, 8
	s_or_b32 s27, s0, s65
	v_lshl_add_u32 v240, s30, 8, v200
	v_or_b32_e32 v216, s27, v202
	s_cmp_eq_u32 s93, 3
	s_cbranch_scc1 .Lst16_fast
	s_cmp_eq_u32 s93, 1
	s_cbranch_scc0 .Llora_no
	s_lshr_b32 s0, s84, 2
	s_cmp_lt_u32 s0, 2
	s_cbranch_scc1 .Llora_fast
; __device__ __forceinline__ size_t xrow(int row) { return (size_t)(row >> 11) * 2049 + 1 + (row & 2047); }
; __device__ __forceinline__ u32x4 pack8(f32x4 a, f32x4 b) { u32x4 w; w.x = pk2(a[0], a[1]); w.y = pk2(a[2], a[3]); w.z = pk2(b[0], b[1]); w.w = pk2(b[2], b[3]); return w; }
;     __device__ __forceinline__ void operator()(const f32x4 (&acc)[2][2][4][2], const Unit& u, int wr, int wc, int fr, int fq) const {
;     ...
;         if (mode == E_RESID) {
;             u32x4 xr[2][4][2];
; #pragma unroll
;             for (int ai = 0; ai < 2; ++ai)
; #pragma unroll
;                 for (int m = 0; m < 4; ++m) {
;                     const int rowg = rowl0 + ai * HALF + m * 16 + pm0 * BM;
;                     const h16* xp = (const h16*)(ws + OFF_X16) + xrow(rowg) * 1024 + colt;
; #pragma unroll
;                     for (int bj = 0; bj < 2; ++bj) xr[ai][m][bj] = *(const u32x4*)(xp + bj * HALF);
;                 }
; #pragma unroll
;             for (int ai = 0; ai < 2; ++ai)
; #pragma unroll
;                 for (int m = 0; m < 4; ++m) {
;                     const int rowg = rowl0 + ai * HALF + m * 16 + pm0 * BM;
;                     float* dp0 = out + (size_t)rowg * 1024 + colt;
;                     h16* hp0 = (h16*)out + (size_t)rowg * 1024 + colt;
; #pragma unroll
;                     for (int bj = 0; bj < 2; ++bj) {
;                         float xf[8]; unpack8(xr[ai][m][bj], xf);
;                         const f32x4 v0 = acc[ai][bj][m][0], v1 = acc[ai][bj][m][1];
;                         f32x4 r0, r1;
; #pragma unroll
;                         for (int jj = 0; jj < 4; ++jj) { r0[jj] = DN_ALPHA * xf[jj] + v0[jj]; r1[jj] = DN_ALPHA * xf[4 + jj] + v1[jj]; }
;                         if (fin) { float* dp = dp0 + bj * HALF; *(f32x4*)dp = r0; *(f32x4*)(dp + 4) = r1; }
;                         else *(u32x4*)(hp0 + bj * HALF) = pack8(r0, r1);
;                     }
.Llora_no:
	s_mov_b64 s[0:1], -1
	s_mov_b64 s[34:35], 0
	s_cmp_lt_i32 s93, 2
	s_mov_b64 s[36:37], 0
	s_cbranch_scc1 .LBB0_831
	s_cmp_eq_u32 s93, 2
	s_mov_b64 s[36:37], -1
	s_cbranch_scc0 .LBB0_830
	s_add_i32 s0, s30, s56
	v_lshl_add_u32 v220, s0, 8, v200
	v_ashrrev_i32_e32 v130, 11, v220
	v_and_b32_e32 v134, 0x7cf, v220
	v_ashrrev_i32_e32 v217, 31, v216
	v_readlane_b32 s0, v249, 8
	v_mul_hi_i32_i24_e32 v131, 0x801, v130
	v_mul_i32_i24_e32 v130, 0x801, v130
	v_add_u32_e32 v196, 1, v134
	v_lshlrev_b64 v[218:219], 1, v[216:217]
	v_readlane_b32 s1, v249, 9
	v_lshl_add_u64 v[132:133], v[130:131], 0, v[196:197]
	v_lshlrev_b64 v[132:133], 11, v[132:133]
	v_lshl_add_u64 v[128:129], s[0:1], 0, v[218:219]
	v_lshl_add_u64 v[132:133], v[128:129], 0, v[132:133]
	v_add_u32_e32 v196, 17, v134
	global_load_dwordx4 v[188:191], v[132:133], off
	global_load_dwordx4 v[184:187], v[132:133], off offset:256
	v_lshl_add_u64 v[132:133], v[130:131], 0, v[196:197]
	v_lshlrev_b64 v[132:133], 11, v[132:133]
	v_lshl_add_u64 v[132:133], v[128:129], 0, v[132:133]
	v_add_u32_e32 v196, 33, v134
	global_load_dwordx4 v[180:183], v[132:133], off
	global_load_dwordx4 v[176:179], v[132:133], off offset:256
	v_lshl_add_u64 v[132:133], v[130:131], 0, v[196:197]
	v_add_u32_e32 v196, 49, v134
	v_lshlrev_b64 v[132:133], 11, v[132:133]
	v_lshl_add_u64 v[130:131], v[130:131], 0, v[196:197]
	v_lshl_add_u64 v[132:133], v[128:129], 0, v[132:133]
	v_lshlrev_b64 v[130:131], 11, v[130:131]
	global_load_dwordx4 v[172:175], v[132:133], off
	global_load_dwordx4 v[168:171], v[132:133], off offset:256
	v_lshl_add_u64 v[130:131], v[128:129], 0, v[130:131]
	v_add_u32_e32 v132, 0x80, v220
	global_load_dwordx4 v[164:167], v[130:131], off
	global_load_dwordx4 v[160:163], v[130:131], off offset:256
	v_ashrrev_i32_e32 v130, 11, v132
	v_and_b32_e32 v132, 0x7cf, v132
	v_mul_hi_i32_i24_e32 v131, 0x801, v130
	v_mul_i32_i24_e32 v130, 0x801, v130
	v_add_u32_e32 v196, 1, v132
	v_lshl_add_u64 v[130:131], v[130:131], 0, v[196:197]
	v_lshlrev_b64 v[130:131], 11, v[130:131]
	v_lshl_add_u64 v[130:131], v[128:129], 0, v[130:131]
	v_add_u32_e32 v132, 0x90, v220
	global_load_dwordx4 v[156:159], v[130:131], off
	global_load_dwordx4 v[152:155], v[130:131], off offset:256
	v_ashrrev_i32_e32 v130, 11, v132
	v_and_b32_e32 v132, 0x7df, v132
	v_mul_hi_i32_i24_e32 v131, 0x801, v130
	v_mul_i32_i24_e32 v130, 0x801, v130
	v_add_u32_e32 v196, 1, v132
	v_lshl_add_u64 v[130:131], v[130:131], 0, v[196:197]
	v_lshlrev_b64 v[130:131], 11, v[130:131]
	v_lshl_add_u64 v[130:131], v[128:129], 0, v[130:131]
	v_add_u32_e32 v132, 0xa0, v220
	global_load_dwordx4 v[148:151], v[130:131], off
	global_load_dwordx4 v[144:147], v[130:131], off offset:256
	v_ashrrev_i32_e32 v130, 11, v132
	v_and_b32_e32 v132, 0x7ef, v132
	v_mul_hi_i32_i24_e32 v131, 0x801, v130
	v_mul_i32_i24_e32 v130, 0x801, v130
	v_add_u32_e32 v196, 1, v132
	v_lshl_add_u64 v[130:131], v[130:131], 0, v[196:197]
	v_lshlrev_b64 v[130:131], 11, v[130:131]
	v_lshl_add_u64 v[130:131], v[128:129], 0, v[130:131]
	v_add_u32_e32 v132, 0xb0, v220
	global_load_dwordx4 v[140:143], v[130:131], off
	global_load_dwordx4 v[136:139], v[130:131], off offset:256
	v_ashrrev_i32_e32 v130, 11, v132
	v_and_b32_e32 v132, 0x7ff, v132
	v_mul_hi_i32_i24_e32 v131, 0x801, v130
	v_mul_i32_i24_e32 v130, 0x801, v130
	v_add_u32_e32 v196, 1, v132
	v_lshl_add_u64 v[130:131], v[130:131], 0, v[196:197]
	v_lshlrev_b64 v[130:131], 11, v[130:131]
	v_lshl_add_u64 v[128:129], v[128:129], 0, v[130:131]
	global_load_dwordx4 v[132:135], v[128:129], off
	s_nop 0
	global_load_dwordx4 v[128:131], v[128:129], off offset:256
	v_ashrrev_i32_e32 v221, 31, v220
	v_readlane_b32 s0, v252, 45
	v_lshlrev_b64 v[192:193], 12, v[220:221]
	v_readlane_b32 s1, v252, 46
	v_readlane_b32 s36, v253, 57
	v_readlane_b32 s37, v253, 58
	v_lshl_add_u64 v[224:225], s[0:1], 0, v[192:193]
	s_mov_b32 s0, 0x3fd744fd
	v_cndmask_b32_e64 v196, 0, 1, s[36:37]
	v_lshl_add_u64 v[222:223], v[216:217], 2, v[224:225]
	s_andn2_b64 vcc, exec, s[36:37]
	s_mov_b64 s[36:37], -1
	s_waitcnt vmcnt(0)
	v_cvt_f32_f16_e32 v192, v188
	v_cvt_f32_f16_sdwa v193, v188 dst_sel:DWORD dst_unused:UNUSED_PAD src0_sel:WORD_1
	v_cvt_f32_f16_e32 v194, v190
	v_cvt_f32_f16_sdwa v195, v190 dst_sel:DWORD dst_unused:UNUSED_PAD src0_sel:WORD_1
	v_cvt_f32_f16_e32 v246, v189
	v_cvt_f32_f16_sdwa v247, v189 dst_sel:DWORD dst_unused:UNUSED_PAD src0_sel:WORD_1
	v_cvt_f32_f16_e32 v190, v191
	v_cvt_f32_f16_sdwa v191, v191 dst_sel:DWORD dst_unused:UNUSED_PAD src0_sel:WORD_1
	v_pk_fma_f32 v[192:193], v[192:193], s[0:1], v[124:125] op_sel_hi:[1,0,1]
	v_pk_fma_f32 v[188:189], v[194:195], s[0:1], v[120:121] op_sel_hi:[1,0,1]
	v_pk_fma_f32 v[194:195], v[246:247], s[0:1], v[126:127] op_sel_hi:[1,0,1]
	v_pk_fma_f32 v[190:191], v[190:191], s[0:1], v[122:123] op_sel_hi:[1,0,1]
	v_cmp_ne_u32_e64 s[0:1], 1, v196
	s_cbranch_vccnz .LBB0_767
	s_mov_b64 s[36:37], 0
	global_store_dwordx4 v[222:223], v[192:195], off
	global_store_dwordx4 v[222:223], v[188:191], off offset:16
